# lean in-proj tiles: the single remaining barrier moved ahead of the last slab's convert+stores
# baseline (speedup 1.0000x reference)
.LBB0_220:
	s_cmp_gt_i32 s7, 0
	s_waitcnt vmcnt(6)
	s_cselect_b32 s8, -1, 2
	s_mul_i32 s9, s7, 0x6000
	s_waitcnt lgkmcnt(0)
	s_add_i32 s8, s8, s7
	v_add_u32_e32 v139, s9, v224
	v_add_u32_e32 v0, s9, v223
	s_mulk_i32 s8, 0x6000
	v_add_u32_e32 v154, v139, v228
	s_barrier
	v_lshl_add_u64 v[170:171], v[144:145], 0, s[2:3]
	v_add_u32_e32 v141, s8, v221
	v_lshl_add_u64 v[174:175], v[142:143], 0, s[2:3]
	v_add_u32_e32 v182, s8, v222
	v_add_u32_e32 v166, v0, v228
	ds_read_b128 v[146:149], v166
	ds_read_b128 v[150:153], v154
	ds_read_b128 v[154:157], v154 offset:2048
	v_lshl_add_u64 v[172:173], v[170:171], 0, s[88:89]
	v_lshl_add_u64 v[176:177], v[174:175], 0, s[88:89]
	v_add_u32_e32 v183, 0x4000, v182
	v_lshl_add_u64 v[178:179], v[170:171], 0, s[90:91]
	v_add_u32_e32 v184, 0x400, v141
	v_lshl_add_u64 v[180:181], v[170:171], 0, s[78:79]
	v_add_u32_e32 v185, 0x800, v141
	ds_read_b128 v[158:161], v166 offset:2048
	ds_read_b128 v[162:165], v166 offset:4096
	ds_read_b128 v[166:169], v166 offset:6144
	s_waitcnt lgkmcnt(3)
	s_setprio 1
	v_mfma_f32_32x32x16_bf16 v[114:129], v[146:149], v[150:153], v[114:129]
	v_mfma_f32_32x32x16_bf16 v[98:113], v[146:149], v[154:157], v[98:113]
	v_readfirstlane_b32 s8, v141
	s_mov_b32 m0, s8
	s_nop 0
	global_load_lds_dwordx4 v[172:173], off
	s_waitcnt lgkmcnt(2)
	v_mfma_f32_32x32x16_bf16 v[82:97], v[158:161], v[150:153], v[82:97]
	v_mfma_f32_32x32x16_bf16 v[66:81], v[158:161], v[154:157], v[66:81]
	v_readfirstlane_b32 s8, v184
	s_mov_b32 m0, s8
	s_nop 0
	global_load_lds_dwordx4 v[178:179], off
	s_waitcnt lgkmcnt(1)
	v_mfma_f32_32x32x16_bf16 v[50:65], v[162:165], v[150:153], v[50:65]
	v_mfma_f32_32x32x16_bf16 v[34:49], v[162:165], v[154:157], v[34:49]
	v_readfirstlane_b32 s8, v185
	s_mov_b32 m0, s8
	s_nop 0
	global_load_lds_dwordx4 v[180:181], off
	s_waitcnt lgkmcnt(0)
	v_mfma_f32_32x32x16_bf16 v[18:33], v[166:169], v[150:153], v[18:33]
	v_mfma_f32_32x32x16_bf16 v[2:17], v[166:169], v[154:157], v[2:17]
	s_setprio 0
	v_add_u32_e32 v0, v0, v229
	v_add_u32_e32 v139, v139, v229
	ds_read_b128 v[146:149], v0
	ds_read_b128 v[150:153], v139
	ds_read_b128 v[154:157], v139 offset:2048
	ds_read_b128 v[158:161], v0 offset:2048
	ds_read_b128 v[162:165], v0 offset:4096
	ds_read_b128 v[166:169], v0 offset:6144
	s_waitcnt lgkmcnt(3)
	s_setprio 1
	v_mfma_f32_32x32x16_bf16 v[114:129], v[146:149], v[150:153], v[114:129]
	v_mfma_f32_32x32x16_bf16 v[98:113], v[146:149], v[154:157], v[98:113]
	v_add_u32_e32 v0, 0xc00, v141
	v_lshl_add_u64 v[146:147], v[170:171], 0, s[76:77]
	v_readfirstlane_b32 s8, v0
	s_mov_b32 m0, s8
	s_nop 0
	global_load_lds_dwordx4 v[146:147], off
	s_waitcnt lgkmcnt(2)
	v_mfma_f32_32x32x16_bf16 v[82:97], v[158:161], v[150:153], v[82:97]
	v_mfma_f32_32x32x16_bf16 v[66:81], v[158:161], v[154:157], v[66:81]
	v_readfirstlane_b32 s8, v183
	s_mov_b32 m0, s8
	s_nop 0
	global_load_lds_dwordx4 v[176:177], off
	s_waitcnt lgkmcnt(1)
	v_mfma_f32_32x32x16_bf16 v[50:65], v[162:165], v[150:153], v[50:65]
	v_mfma_f32_32x32x16_bf16 v[34:49], v[162:165], v[154:157], v[34:49]
	v_add_u32_e32 v0, 0x4400, v182
	v_lshl_add_u64 v[146:147], v[174:175], 0, s[90:91]
	v_readfirstlane_b32 s8, v0
	s_mov_b32 m0, s8
	s_nop 0
	global_load_lds_dwordx4 v[146:147], off
	s_waitcnt lgkmcnt(0)
	v_mfma_f32_32x32x16_bf16 v[18:33], v[166:169], v[150:153], v[18:33]
	v_mfma_f32_32x32x16_bf16 v[2:17], v[166:169], v[154:157], v[2:17]
	s_setprio 0
	s_add_i32 s8, s7, 1
	s_cmp_lt_i32 s7, 2
	s_cselect_b32 s7, s8, 0
	s_add_u32 s2, s2, 0x80
	s_addc_u32 s3, s3, 0
	s_cmpk_eq_i32 s2, 0xf00
	s_cbranch_scc0 .LBB0_220
	s_waitcnt vmcnt(6)
	s_mul_i32 s2, s7, 0x6000
	s_waitcnt lgkmcnt(0)
	v_add_u32_e32 v139, s2, v224
	v_add_u32_e32 v0, s2, v223
	v_add_u32_e32 v150, v139, v228
	s_barrier
	v_add_u32_e32 v141, v0, v228
	ds_read_b128 v[142:145], v141
	ds_read_b128 v[146:149], v150
	ds_read_b128 v[150:153], v150 offset:2048
	ds_read_b128 v[154:157], v141 offset:2048
	ds_read_b128 v[158:161], v141 offset:4096
	ds_read_b128 v[162:165], v141 offset:6144
	s_waitcnt lgkmcnt(3)
	s_setprio 1
	v_mfma_f32_32x32x16_bf16 v[114:129], v[142:145], v[146:149], v[114:129]
	v_mfma_f32_32x32x16_bf16 v[98:113], v[142:145], v[150:153], v[98:113]
	s_waitcnt lgkmcnt(2)
	v_mfma_f32_32x32x16_bf16 v[82:97], v[154:157], v[146:149], v[82:97]
	v_mfma_f32_32x32x16_bf16 v[66:81], v[154:157], v[150:153], v[66:81]
	s_waitcnt lgkmcnt(1)
	v_mfma_f32_32x32x16_bf16 v[50:65], v[158:161], v[146:149], v[50:65]
	v_mfma_f32_32x32x16_bf16 v[34:49], v[158:161], v[150:153], v[34:49]
	s_waitcnt lgkmcnt(0)
	v_mfma_f32_32x32x16_bf16 v[18:33], v[162:165], v[146:149], v[18:33]
	v_mfma_f32_32x32x16_bf16 v[2:17], v[162:165], v[150:153], v[2:17]
	s_setprio 0
	v_add_u32_e32 v0, v0, v229
	v_add_u32_e32 v139, v139, v229
	ds_read_b128 v[142:145], v0
	ds_read_b128 v[146:149], v139
	ds_read_b128 v[150:153], v139 offset:2048
	ds_read_b128 v[154:157], v0 offset:2048
	ds_read_b128 v[158:161], v0 offset:4096
	ds_read_b128 v[162:165], v0 offset:6144
	s_waitcnt lgkmcnt(3)
	s_setprio 1
	v_mfma_f32_32x32x16_bf16 v[114:129], v[142:145], v[146:149], v[114:129]
	v_mfma_f32_32x32x16_bf16 v[98:113], v[142:145], v[150:153], v[98:113]
	s_waitcnt lgkmcnt(2)
	v_mfma_f32_32x32x16_bf16 v[82:97], v[154:157], v[146:149], v[82:97]
	v_mfma_f32_32x32x16_bf16 v[66:81], v[154:157], v[150:153], v[66:81]
	s_waitcnt lgkmcnt(1)
	v_mfma_f32_32x32x16_bf16 v[50:65], v[158:161], v[146:149], v[50:65]
	v_mfma_f32_32x32x16_bf16 v[34:49], v[158:161], v[150:153], v[34:49]
	s_waitcnt lgkmcnt(0)
	v_mfma_f32_32x32x16_bf16 v[18:33], v[162:165], v[146:149], v[18:33]
	v_mfma_f32_32x32x16_bf16 v[2:17], v[162:165], v[150:153], v[2:17]
	s_setprio 0
	s_waitcnt vmcnt(0)
	s_waitcnt lgkmcnt(0)
	s_barrier
	ds_read_b128 v[142:145], v232
	ds_read_b128 v[146:149], v233
	ds_read_b128 v[150:153], v233 offset:2048
	ds_read_b128 v[154:157], v232 offset:2048
	ds_read_b128 v[158:161], v232 offset:4096
	ds_read_b128 v[162:165], v232 offset:6144
	s_waitcnt lgkmcnt(3)
	s_setprio 1
	v_mfma_f32_32x32x16_bf16 v[114:129], v[142:145], v[146:149], v[114:129]
	v_mfma_f32_32x32x16_bf16 v[98:113], v[142:145], v[150:153], v[98:113]
	s_waitcnt lgkmcnt(2)
	v_mfma_f32_32x32x16_bf16 v[82:97], v[154:157], v[146:149], v[82:97]
	v_mfma_f32_32x32x16_bf16 v[66:81], v[154:157], v[150:153], v[66:81]
	s_waitcnt lgkmcnt(1)
	v_mfma_f32_32x32x16_bf16 v[50:65], v[158:161], v[146:149], v[50:65]
	v_mfma_f32_32x32x16_bf16 v[34:49], v[158:161], v[150:153], v[34:49]
	s_waitcnt lgkmcnt(0)
	v_mfma_f32_32x32x16_bf16 v[18:33], v[162:165], v[146:149], v[18:33]
	v_mfma_f32_32x32x16_bf16 v[2:17], v[162:165], v[150:153], v[2:17]
	s_setprio 0
	ds_read_b128 v[142:145], v234
	ds_read_b128 v[146:149], v235
	ds_read_b128 v[150:153], v235 offset:2048
	ds_read_b128 v[154:157], v234 offset:2048
	ds_read_b128 v[158:161], v234 offset:4096
	ds_read_b128 v[162:165], v234 offset:6144
	s_waitcnt lgkmcnt(3)
	s_setprio 1
	v_mfma_f32_32x32x16_bf16 v[114:129], v[142:145], v[146:149], v[114:129]
	v_mfma_f32_32x32x16_bf16 v[98:113], v[142:145], v[150:153], v[98:113]
	s_waitcnt lgkmcnt(2)
	v_mfma_f32_32x32x16_bf16 v[82:97], v[154:157], v[146:149], v[82:97]
	v_mfma_f32_32x32x16_bf16 v[66:81], v[154:157], v[150:153], v[66:81]
	s_waitcnt lgkmcnt(1)
	v_mfma_f32_32x32x16_bf16 v[50:65], v[158:161], v[146:149], v[50:65]
	v_mfma_f32_32x32x16_bf16 v[34:49], v[158:161], v[150:153], v[34:49]
	s_waitcnt lgkmcnt(0)
	v_mfma_f32_32x32x16_bf16 v[18:33], v[162:165], v[146:149], v[18:33]
	v_mfma_f32_32x32x16_bf16 v[2:17], v[162:165], v[150:153], v[2:17]
	s_setprio 0
	s_cmp_gt_i32 s4, 3
	s_cselect_b64 s[30:31], -1, 0
	s_add_i32 s2, s4, -8
	s_cmp_gt_u32 s2, 5
	s_cselect_b64 s[98:99], -1, 0
	s_and_b32 s2, s4, 0x7ffffffc
	s_cmp_lg_u32 s2, 20
	v_add_u32_e32 v238, s5, v225
	s_cselect_b64 s[2:3], -1, 0
	s_and_b32 s5, s4, 0x7ffffffe
	s_cmp_eq_u32 s5, 6
	s_cselect_b64 s[82:83], -1, 0
	s_sub_i32 s5, s4, 17
	v_add_u32_e32 v239, 0x800, v230
	v_add_u32_e32 v240, 0x1000, v230
	v_add_u32_e32 v241, 0x1800, v230
	s_mov_b32 s8, 0x0701c030
	s_mov_b32 s34, 0x380e00c0
	s_lshr_b32 s8, s8, s4
	s_lshr_b32 s34, s34, s4
	s_and_b32 s8, s8, 1
	s_and_b32 s34, s34, 1
	s_or_b32 s7, s8, s34
	s_cmp_eq_u32 s7, 0
	s_cbranch_scc1 .Lmy_g0e_std
	v_and_b32_e32 v151, 63, v200
	v_lshrrev_b32_e32 v150, 5, v151
	v_and_b32_e32 v146, 31, v151
	v_lshrrev_b32_e32 v147, 6, v200
	v_lshrrev_b32_e32 v152, 1, v147
	v_and_b32_e32 v148, 1, v147
	v_mul_u32_u24_e32 v147, 0x2200, v147
	s_movk_i32 s6, 0x7c00
	v_mad_u32_u24 v147, v152, s6, v147
	v_lshlrev_b32_e32 v146, 2, v146
	s_movk_i32 s6, 0x440
	v_mad_u32_u24 v146, v150, s6, v146
	v_add_u32_e32 v146, v146, v147
	v_lshrrev_b32_e32 v150, 3, v151
	v_and_b32_e32 v149, 7, v151
	s_movk_i32 s6, 0x110
	v_mad_u32_u24 v147, v150, s6, v147
	v_lshl_add_u32 v147, v149, 5, v147
	v_lshl_add_u32 v152, v152, 7, s32
	v_add_u32_e32 v152, v152, v150
	s_lshl_b32 s6, s4, 7
	v_lshl_add_u32 v148, v148, 6, s6
	v_lshl_add_u32 v148, v149, 3, v148
	v_lshlrev_b32_e32 v148, 1, v148
	v_mul_u32_u24_e32 v152, 0x1e00, v152
	v_add_u32_e32 v148, v148, v152
	s_mov_b64 s[8:9], s[64:65]
	s_cmp_eq_u32 s34, 1
	s_cbranch_scc1 .Lmy_g0e_gate
	ds_write2_b32 v146, v114, v98 offset0:0 offset1:32
	ds_write2_b32 v146, v115, v99 offset0:68 offset1:100
	ds_write2_b32 v146, v116, v100 offset0:136 offset1:168
	ds_write2_b32 v146, v117, v101 offset0:204 offset1:236
	v_add_u32_e32 v146, 0x880, v146
	ds_write2_b32 v146, v118, v102 offset0:0 offset1:32
	ds_write2_b32 v146, v119, v103 offset0:68 offset1:100
	ds_write2_b32 v146, v120, v104 offset0:136 offset1:168
	ds_write2_b32 v146, v121, v105 offset0:204 offset1:236
	v_add_u32_e32 v146, 0x880, v146
	ds_write2_b32 v146, v122, v106 offset0:0 offset1:32
	ds_write2_b32 v146, v123, v107 offset0:68 offset1:100
	ds_write2_b32 v146, v124, v108 offset0:136 offset1:168
	ds_write2_b32 v146, v125, v109 offset0:204 offset1:236
	v_add_u32_e32 v146, 0x880, v146
	ds_write2_b32 v146, v126, v110 offset0:0 offset1:32
	ds_write2_b32 v146, v127, v111 offset0:68 offset1:100
	ds_write2_b32 v146, v128, v112 offset0:136 offset1:168
	ds_write2_b32 v146, v129, v113 offset0:204 offset1:236
	v_subrev_u32_e32 v146, 0x1980, v146
	s_waitcnt lgkmcnt(0)
	ds_read_b128 v[98:101], v147
	ds_read_b128 v[102:105], v147 offset:16
	ds_read_b128 v[106:109], v147 offset:2176
	ds_read_b128 v[110:113], v147 offset:2192
	ds_read_b128 v[114:117], v147 offset:4352
	ds_read_b128 v[118:121], v147 offset:4368
	ds_read_b128 v[122:125], v147 offset:6528
	ds_read_b128 v[126:129], v147 offset:6544
	s_waitcnt lgkmcnt(6)
	v_cvt_pk_bf16_f32 v154, v98, v99
	v_cvt_pk_bf16_f32 v155, v100, v101
	v_cvt_pk_bf16_f32 v156, v102, v103
	v_cvt_pk_bf16_f32 v157, v104, v105
	global_store_dwordx4 v148, v[154:157], s[8:9]
	s_add_u32 s8, s8, 0xf000
	s_addc_u32 s9, s9, 0
	s_waitcnt lgkmcnt(4)
	v_cvt_pk_bf16_f32 v158, v106, v107
	v_cvt_pk_bf16_f32 v159, v108, v109
	v_cvt_pk_bf16_f32 v160, v110, v111
	v_cvt_pk_bf16_f32 v161, v112, v113
	global_store_dwordx4 v148, v[158:161], s[8:9]
	s_add_u32 s8, s8, 0xf000
	s_addc_u32 s9, s9, 0
	s_waitcnt lgkmcnt(2)
	v_cvt_pk_bf16_f32 v162, v114, v115
	v_cvt_pk_bf16_f32 v163, v116, v117
	v_cvt_pk_bf16_f32 v164, v118, v119
	v_cvt_pk_bf16_f32 v165, v120, v121
	global_store_dwordx4 v148, v[162:165], s[8:9]
	s_add_u32 s8, s8, 0xf000
	s_addc_u32 s9, s9, 0
	s_waitcnt lgkmcnt(0)
	v_cvt_pk_bf16_f32 v166, v122, v123
	v_cvt_pk_bf16_f32 v167, v124, v125
	v_cvt_pk_bf16_f32 v168, v126, v127
	v_cvt_pk_bf16_f32 v169, v128, v129
	global_store_dwordx4 v148, v[166:169], s[8:9]
	s_add_u32 s8, s8, 0xf000
	s_addc_u32 s9, s9, 0
	ds_write2_b32 v146, v82, v66 offset0:0 offset1:32
	ds_write2_b32 v146, v83, v67 offset0:68 offset1:100
	ds_write2_b32 v146, v84, v68 offset0:136 offset1:168
	ds_write2_b32 v146, v85, v69 offset0:204 offset1:236
	v_add_u32_e32 v146, 0x880, v146
	ds_write2_b32 v146, v86, v70 offset0:0 offset1:32
	ds_write2_b32 v146, v87, v71 offset0:68 offset1:100
	ds_write2_b32 v146, v88, v72 offset0:136 offset1:168
	ds_write2_b32 v146, v89, v73 offset0:204 offset1:236
	v_add_u32_e32 v146, 0x880, v146
	ds_write2_b32 v146, v90, v74 offset0:0 offset1:32
	ds_write2_b32 v146, v91, v75 offset0:68 offset1:100
	ds_write2_b32 v146, v92, v76 offset0:136 offset1:168
	ds_write2_b32 v146, v93, v77 offset0:204 offset1:236
	v_add_u32_e32 v146, 0x880, v146
	ds_write2_b32 v146, v94, v78 offset0:0 offset1:32
	ds_write2_b32 v146, v95, v79 offset0:68 offset1:100
	ds_write2_b32 v146, v96, v80 offset0:136 offset1:168
	ds_write2_b32 v146, v97, v81 offset0:204 offset1:236
	v_subrev_u32_e32 v146, 0x1980, v146
	s_waitcnt lgkmcnt(0)
	ds_read_b128 v[66:69], v147
	ds_read_b128 v[70:73], v147 offset:16
	ds_read_b128 v[74:77], v147 offset:2176
	ds_read_b128 v[78:81], v147 offset:2192
	ds_read_b128 v[82:85], v147 offset:4352
	ds_read_b128 v[86:89], v147 offset:4368
	ds_read_b128 v[90:93], v147 offset:6528
	ds_read_b128 v[94:97], v147 offset:6544
	s_waitcnt lgkmcnt(6)
	v_cvt_pk_bf16_f32 v154, v66, v67
	v_cvt_pk_bf16_f32 v155, v68, v69
	v_cvt_pk_bf16_f32 v156, v70, v71
	v_cvt_pk_bf16_f32 v157, v72, v73
	global_store_dwordx4 v148, v[154:157], s[8:9]
	s_add_u32 s8, s8, 0xf000
	s_addc_u32 s9, s9, 0
	s_waitcnt lgkmcnt(4)
	v_cvt_pk_bf16_f32 v158, v74, v75
	v_cvt_pk_bf16_f32 v159, v76, v77
	v_cvt_pk_bf16_f32 v160, v78, v79
	v_cvt_pk_bf16_f32 v161, v80, v81
	global_store_dwordx4 v148, v[158:161], s[8:9]
	s_add_u32 s8, s8, 0xf000
	s_addc_u32 s9, s9, 0
	s_waitcnt lgkmcnt(2)
	v_cvt_pk_bf16_f32 v162, v82, v83
	v_cvt_pk_bf16_f32 v163, v84, v85
	v_cvt_pk_bf16_f32 v164, v86, v87
	v_cvt_pk_bf16_f32 v165, v88, v89
	global_store_dwordx4 v148, v[162:165], s[8:9]
	s_add_u32 s8, s8, 0xf000
	s_addc_u32 s9, s9, 0
	s_waitcnt lgkmcnt(0)
	v_cvt_pk_bf16_f32 v166, v90, v91
	v_cvt_pk_bf16_f32 v167, v92, v93
	v_cvt_pk_bf16_f32 v168, v94, v95
	v_cvt_pk_bf16_f32 v169, v96, v97
	global_store_dwordx4 v148, v[166:169], s[8:9]
	s_add_u32 s8, s8, 0xf000
	s_addc_u32 s9, s9, 0
	ds_write2_b32 v146, v50, v34 offset0:0 offset1:32
	ds_write2_b32 v146, v51, v35 offset0:68 offset1:100
	ds_write2_b32 v146, v52, v36 offset0:136 offset1:168
	ds_write2_b32 v146, v53, v37 offset0:204 offset1:236
	v_add_u32_e32 v146, 0x880, v146
	ds_write2_b32 v146, v54, v38 offset0:0 offset1:32
	ds_write2_b32 v146, v55, v39 offset0:68 offset1:100
	ds_write2_b32 v146, v56, v40 offset0:136 offset1:168
	ds_write2_b32 v146, v57, v41 offset0:204 offset1:236
	v_add_u32_e32 v146, 0x880, v146
	ds_write2_b32 v146, v58, v42 offset0:0 offset1:32
	ds_write2_b32 v146, v59, v43 offset0:68 offset1:100
	ds_write2_b32 v146, v60, v44 offset0:136 offset1:168
	ds_write2_b32 v146, v61, v45 offset0:204 offset1:236
	v_add_u32_e32 v146, 0x880, v146
	ds_write2_b32 v146, v62, v46 offset0:0 offset1:32
	ds_write2_b32 v146, v63, v47 offset0:68 offset1:100
	ds_write2_b32 v146, v64, v48 offset0:136 offset1:168
	ds_write2_b32 v146, v65, v49 offset0:204 offset1:236
	v_subrev_u32_e32 v146, 0x1980, v146
	s_waitcnt lgkmcnt(0)
	ds_read_b128 v[34:37], v147
	ds_read_b128 v[38:41], v147 offset:16
	ds_read_b128 v[42:45], v147 offset:2176
	ds_read_b128 v[46:49], v147 offset:2192
	ds_read_b128 v[50:53], v147 offset:4352
	ds_read_b128 v[54:57], v147 offset:4368
	ds_read_b128 v[58:61], v147 offset:6528
	ds_read_b128 v[62:65], v147 offset:6544
	s_waitcnt lgkmcnt(6)
	v_cvt_pk_bf16_f32 v154, v34, v35
	v_cvt_pk_bf16_f32 v155, v36, v37
	v_cvt_pk_bf16_f32 v156, v38, v39
	v_cvt_pk_bf16_f32 v157, v40, v41
	global_store_dwordx4 v148, v[154:157], s[8:9]
	s_add_u32 s8, s8, 0xf000
	s_addc_u32 s9, s9, 0
	s_waitcnt lgkmcnt(4)
	v_cvt_pk_bf16_f32 v158, v42, v43
	v_cvt_pk_bf16_f32 v159, v44, v45
	v_cvt_pk_bf16_f32 v160, v46, v47
	v_cvt_pk_bf16_f32 v161, v48, v49
	global_store_dwordx4 v148, v[158:161], s[8:9]
	s_add_u32 s8, s8, 0xf000
	s_addc_u32 s9, s9, 0
	s_waitcnt lgkmcnt(2)
	v_cvt_pk_bf16_f32 v162, v50, v51
	v_cvt_pk_bf16_f32 v163, v52, v53
	v_cvt_pk_bf16_f32 v164, v54, v55
	v_cvt_pk_bf16_f32 v165, v56, v57
	global_store_dwordx4 v148, v[162:165], s[8:9]
	s_add_u32 s8, s8, 0xf000
	s_addc_u32 s9, s9, 0
	s_waitcnt lgkmcnt(0)
	v_cvt_pk_bf16_f32 v166, v58, v59
	v_cvt_pk_bf16_f32 v167, v60, v61
	v_cvt_pk_bf16_f32 v168, v62, v63
	v_cvt_pk_bf16_f32 v169, v64, v65
	global_store_dwordx4 v148, v[166:169], s[8:9]
	s_add_u32 s8, s8, 0xf000
	s_addc_u32 s9, s9, 0
	ds_write2_b32 v146, v18, v2 offset0:0 offset1:32
	ds_write2_b32 v146, v19, v3 offset0:68 offset1:100
	ds_write2_b32 v146, v20, v4 offset0:136 offset1:168
	ds_write2_b32 v146, v21, v5 offset0:204 offset1:236
	v_add_u32_e32 v146, 0x880, v146
	ds_write2_b32 v146, v22, v6 offset0:0 offset1:32
	ds_write2_b32 v146, v23, v7 offset0:68 offset1:100
	ds_write2_b32 v146, v24, v8 offset0:136 offset1:168
	ds_write2_b32 v146, v25, v9 offset0:204 offset1:236
	v_add_u32_e32 v146, 0x880, v146
	ds_write2_b32 v146, v26, v10 offset0:0 offset1:32
	ds_write2_b32 v146, v27, v11 offset0:68 offset1:100
	ds_write2_b32 v146, v28, v12 offset0:136 offset1:168
	ds_write2_b32 v146, v29, v13 offset0:204 offset1:236
	v_add_u32_e32 v146, 0x880, v146
	ds_write2_b32 v146, v30, v14 offset0:0 offset1:32
	ds_write2_b32 v146, v31, v15 offset0:68 offset1:100
	ds_write2_b32 v146, v32, v16 offset0:136 offset1:168
	ds_write2_b32 v146, v33, v17 offset0:204 offset1:236
	v_subrev_u32_e32 v146, 0x1980, v146
	s_waitcnt lgkmcnt(0)
	ds_read_b128 v[2:5], v147
	ds_read_b128 v[6:9], v147 offset:16
	ds_read_b128 v[10:13], v147 offset:2176
	ds_read_b128 v[14:17], v147 offset:2192
	ds_read_b128 v[18:21], v147 offset:4352
	ds_read_b128 v[22:25], v147 offset:4368
	ds_read_b128 v[26:29], v147 offset:6528
	ds_read_b128 v[30:33], v147 offset:6544
	s_waitcnt lgkmcnt(0)
	s_barrier
	v_cvt_pk_bf16_f32 v154, v2, v3
	v_cvt_pk_bf16_f32 v155, v4, v5
	v_cvt_pk_bf16_f32 v156, v6, v7
	v_cvt_pk_bf16_f32 v157, v8, v9
	global_store_dwordx4 v148, v[154:157], s[8:9]
	s_add_u32 s8, s8, 0xf000
	s_addc_u32 s9, s9, 0
	v_cvt_pk_bf16_f32 v158, v10, v11
	v_cvt_pk_bf16_f32 v159, v12, v13
	v_cvt_pk_bf16_f32 v160, v14, v15
	v_cvt_pk_bf16_f32 v161, v16, v17
	global_store_dwordx4 v148, v[158:161], s[8:9]
	s_add_u32 s8, s8, 0xf000
	s_addc_u32 s9, s9, 0
	v_cvt_pk_bf16_f32 v162, v18, v19
	v_cvt_pk_bf16_f32 v163, v20, v21
	v_cvt_pk_bf16_f32 v164, v22, v23
	v_cvt_pk_bf16_f32 v165, v24, v25
	global_store_dwordx4 v148, v[162:165], s[8:9]
	s_add_u32 s8, s8, 0xf000
	s_addc_u32 s9, s9, 0
	v_cvt_pk_bf16_f32 v166, v26, v27
	v_cvt_pk_bf16_f32 v167, v28, v29
	v_cvt_pk_bf16_f32 v168, v30, v31
	v_cvt_pk_bf16_f32 v169, v32, v33
	global_store_dwordx4 v148, v[166:169], s[8:9]
	s_add_u32 s8, s8, 0xf000
	s_addc_u32 s9, s9, 0
	s_add_i32 s70, s70, s10
	s_cmp_lt_i32 s70, s71
	s_cbranch_scc0 .LBB0_209
	s_branch .LBB0_215
.Lmy_g0e_gate:
	ds_write2_b32 v146, v114, v98 offset0:0 offset1:32
	ds_write2_b32 v146, v115, v99 offset0:68 offset1:100
	ds_write2_b32 v146, v116, v100 offset0:136 offset1:168
	ds_write2_b32 v146, v117, v101 offset0:204 offset1:236
	v_add_u32_e32 v146, 0x880, v146
	ds_write2_b32 v146, v118, v102 offset0:0 offset1:32
	ds_write2_b32 v146, v119, v103 offset0:68 offset1:100
	ds_write2_b32 v146, v120, v104 offset0:136 offset1:168
	ds_write2_b32 v146, v121, v105 offset0:204 offset1:236
	v_add_u32_e32 v146, 0x880, v146
	ds_write2_b32 v146, v122, v106 offset0:0 offset1:32
	ds_write2_b32 v146, v123, v107 offset0:68 offset1:100
	ds_write2_b32 v146, v124, v108 offset0:136 offset1:168
	ds_write2_b32 v146, v125, v109 offset0:204 offset1:236
	v_add_u32_e32 v146, 0x880, v146
	ds_write2_b32 v146, v126, v110 offset0:0 offset1:32
	ds_write2_b32 v146, v127, v111 offset0:68 offset1:100
	ds_write2_b32 v146, v128, v112 offset0:136 offset1:168
	ds_write2_b32 v146, v129, v113 offset0:204 offset1:236
	v_subrev_u32_e32 v146, 0x1980, v146
	s_waitcnt lgkmcnt(0)
	ds_read_b128 v[98:101], v147
	ds_read_b128 v[102:105], v147 offset:16
	ds_read_b128 v[106:109], v147 offset:2176
	ds_read_b128 v[110:113], v147 offset:2192
	ds_read_b128 v[114:117], v147 offset:4352
	ds_read_b128 v[118:121], v147 offset:4368
	ds_read_b128 v[122:125], v147 offset:6528
	ds_read_b128 v[126:129], v147 offset:6544
	s_waitcnt lgkmcnt(6)
	v_mul_f32_e32 v170, 0xbfb8aa3b, v98
	v_mul_f32_e32 v171, 0xbfb8aa3b, v99
	v_mul_f32_e32 v172, 0xbfb8aa3b, v100
	v_mul_f32_e32 v173, 0xbfb8aa3b, v101
	v_exp_f32_e32 v170, v170
	v_exp_f32_e32 v171, v171
	v_exp_f32_e32 v172, v172
	v_exp_f32_e32 v173, v173
	v_add_f32_e32 v170, 1.0, v170
	v_add_f32_e32 v171, 1.0, v171
	v_add_f32_e32 v172, 1.0, v172
	v_add_f32_e32 v173, 1.0, v173
	v_rcp_f32_e32 v170, v170
	v_rcp_f32_e32 v171, v171
	v_rcp_f32_e32 v172, v172
	v_rcp_f32_e32 v173, v173
	s_nop 0
	v_mul_f32_e32 v98, v98, v170
	v_mul_f32_e32 v99, v99, v171
	v_mul_f32_e32 v100, v100, v172
	v_mul_f32_e32 v101, v101, v173
	v_cvt_pk_bf16_f32 v154, v98, v99
	v_cvt_pk_bf16_f32 v155, v100, v101
	v_mul_f32_e32 v170, 0xbfb8aa3b, v102
	v_mul_f32_e32 v171, 0xbfb8aa3b, v103
	v_mul_f32_e32 v172, 0xbfb8aa3b, v104
	v_mul_f32_e32 v173, 0xbfb8aa3b, v105
	v_exp_f32_e32 v170, v170
	v_exp_f32_e32 v171, v171
	v_exp_f32_e32 v172, v172
	v_exp_f32_e32 v173, v173
	v_add_f32_e32 v170, 1.0, v170
	v_add_f32_e32 v171, 1.0, v171
	v_add_f32_e32 v172, 1.0, v172
	v_add_f32_e32 v173, 1.0, v173
	v_rcp_f32_e32 v170, v170
	v_rcp_f32_e32 v171, v171
	v_rcp_f32_e32 v172, v172
	v_rcp_f32_e32 v173, v173
	s_nop 0
	v_mul_f32_e32 v102, v102, v170
	v_mul_f32_e32 v103, v103, v171
	v_mul_f32_e32 v104, v104, v172
	v_mul_f32_e32 v105, v105, v173
	v_cvt_pk_bf16_f32 v156, v102, v103
	v_cvt_pk_bf16_f32 v157, v104, v105
	global_store_dwordx4 v148, v[154:157], s[8:9]
	s_add_u32 s8, s8, 0xf000
	s_addc_u32 s9, s9, 0
	s_waitcnt lgkmcnt(4)
	v_mul_f32_e32 v170, 0xbfb8aa3b, v106
	v_mul_f32_e32 v171, 0xbfb8aa3b, v107
	v_mul_f32_e32 v172, 0xbfb8aa3b, v108
	v_mul_f32_e32 v173, 0xbfb8aa3b, v109
	v_exp_f32_e32 v170, v170
	v_exp_f32_e32 v171, v171
	v_exp_f32_e32 v172, v172
	v_exp_f32_e32 v173, v173
	v_add_f32_e32 v170, 1.0, v170
	v_add_f32_e32 v171, 1.0, v171
	v_add_f32_e32 v172, 1.0, v172
	v_add_f32_e32 v173, 1.0, v173
	v_rcp_f32_e32 v170, v170
	v_rcp_f32_e32 v171, v171
	v_rcp_f32_e32 v172, v172
	v_rcp_f32_e32 v173, v173
	s_nop 0
	v_mul_f32_e32 v106, v106, v170
	v_mul_f32_e32 v107, v107, v171
	v_mul_f32_e32 v108, v108, v172
	v_mul_f32_e32 v109, v109, v173
	v_cvt_pk_bf16_f32 v158, v106, v107
	v_cvt_pk_bf16_f32 v159, v108, v109
	v_mul_f32_e32 v170, 0xbfb8aa3b, v110
	v_mul_f32_e32 v171, 0xbfb8aa3b, v111
	v_mul_f32_e32 v172, 0xbfb8aa3b, v112
	v_mul_f32_e32 v173, 0xbfb8aa3b, v113
	v_exp_f32_e32 v170, v170
	v_exp_f32_e32 v171, v171
	v_exp_f32_e32 v172, v172
	v_exp_f32_e32 v173, v173
	v_add_f32_e32 v170, 1.0, v170
	v_add_f32_e32 v171, 1.0, v171
	v_add_f32_e32 v172, 1.0, v172
	v_add_f32_e32 v173, 1.0, v173
	v_rcp_f32_e32 v170, v170
	v_rcp_f32_e32 v171, v171
	v_rcp_f32_e32 v172, v172
	v_rcp_f32_e32 v173, v173
	s_nop 0
	v_mul_f32_e32 v110, v110, v170
	v_mul_f32_e32 v111, v111, v171
	v_mul_f32_e32 v112, v112, v172
	v_mul_f32_e32 v113, v113, v173
	v_cvt_pk_bf16_f32 v160, v110, v111
	v_cvt_pk_bf16_f32 v161, v112, v113
	global_store_dwordx4 v148, v[158:161], s[8:9]
	s_add_u32 s8, s8, 0xf000
	s_addc_u32 s9, s9, 0
	s_waitcnt lgkmcnt(2)
	v_mul_f32_e32 v170, 0xbfb8aa3b, v114
	v_mul_f32_e32 v171, 0xbfb8aa3b, v115
	v_mul_f32_e32 v172, 0xbfb8aa3b, v116
	v_mul_f32_e32 v173, 0xbfb8aa3b, v117
	v_exp_f32_e32 v170, v170
	v_exp_f32_e32 v171, v171
	v_exp_f32_e32 v172, v172
	v_exp_f32_e32 v173, v173
	v_add_f32_e32 v170, 1.0, v170
	v_add_f32_e32 v171, 1.0, v171
	v_add_f32_e32 v172, 1.0, v172
	v_add_f32_e32 v173, 1.0, v173
	v_rcp_f32_e32 v170, v170
	v_rcp_f32_e32 v171, v171
	v_rcp_f32_e32 v172, v172
	v_rcp_f32_e32 v173, v173
	s_nop 0
	v_mul_f32_e32 v114, v114, v170
	v_mul_f32_e32 v115, v115, v171
	v_mul_f32_e32 v116, v116, v172
	v_mul_f32_e32 v117, v117, v173
	v_cvt_pk_bf16_f32 v162, v114, v115
	v_cvt_pk_bf16_f32 v163, v116, v117
	v_mul_f32_e32 v170, 0xbfb8aa3b, v118
	v_mul_f32_e32 v171, 0xbfb8aa3b, v119
	v_mul_f32_e32 v172, 0xbfb8aa3b, v120
	v_mul_f32_e32 v173, 0xbfb8aa3b, v121
	v_exp_f32_e32 v170, v170
	v_exp_f32_e32 v171, v171
	v_exp_f32_e32 v172, v172
	v_exp_f32_e32 v173, v173
	v_add_f32_e32 v170, 1.0, v170
	v_add_f32_e32 v171, 1.0, v171
	v_add_f32_e32 v172, 1.0, v172
	v_add_f32_e32 v173, 1.0, v173
	v_rcp_f32_e32 v170, v170
	v_rcp_f32_e32 v171, v171
	v_rcp_f32_e32 v172, v172
	v_rcp_f32_e32 v173, v173
	s_nop 0
	v_mul_f32_e32 v118, v118, v170
	v_mul_f32_e32 v119, v119, v171
	v_mul_f32_e32 v120, v120, v172
	v_mul_f32_e32 v121, v121, v173
	v_cvt_pk_bf16_f32 v164, v118, v119
	v_cvt_pk_bf16_f32 v165, v120, v121
	global_store_dwordx4 v148, v[162:165], s[8:9]
	s_add_u32 s8, s8, 0xf000
	s_addc_u32 s9, s9, 0
	s_waitcnt lgkmcnt(0)
	v_mul_f32_e32 v170, 0xbfb8aa3b, v122
	v_mul_f32_e32 v171, 0xbfb8aa3b, v123
	v_mul_f32_e32 v172, 0xbfb8aa3b, v124
	v_mul_f32_e32 v173, 0xbfb8aa3b, v125
	v_exp_f32_e32 v170, v170
	v_exp_f32_e32 v171, v171
	v_exp_f32_e32 v172, v172
	v_exp_f32_e32 v173, v173
	v_add_f32_e32 v170, 1.0, v170
	v_add_f32_e32 v171, 1.0, v171
	v_add_f32_e32 v172, 1.0, v172
	v_add_f32_e32 v173, 1.0, v173
	v_rcp_f32_e32 v170, v170
	v_rcp_f32_e32 v171, v171
	v_rcp_f32_e32 v172, v172
	v_rcp_f32_e32 v173, v173
	s_nop 0
	v_mul_f32_e32 v122, v122, v170
	v_mul_f32_e32 v123, v123, v171
	v_mul_f32_e32 v124, v124, v172
	v_mul_f32_e32 v125, v125, v173
	v_cvt_pk_bf16_f32 v166, v122, v123
	v_cvt_pk_bf16_f32 v167, v124, v125
	v_mul_f32_e32 v170, 0xbfb8aa3b, v126
	v_mul_f32_e32 v171, 0xbfb8aa3b, v127
	v_mul_f32_e32 v172, 0xbfb8aa3b, v128
	v_mul_f32_e32 v173, 0xbfb8aa3b, v129
	v_exp_f32_e32 v170, v170
	v_exp_f32_e32 v171, v171
	v_exp_f32_e32 v172, v172
	v_exp_f32_e32 v173, v173
	v_add_f32_e32 v170, 1.0, v170
	v_add_f32_e32 v171, 1.0, v171
	v_add_f32_e32 v172, 1.0, v172
	v_add_f32_e32 v173, 1.0, v173
	v_rcp_f32_e32 v170, v170
	v_rcp_f32_e32 v171, v171
	v_rcp_f32_e32 v172, v172
	v_rcp_f32_e32 v173, v173
	s_nop 0
	v_mul_f32_e32 v126, v126, v170
	v_mul_f32_e32 v127, v127, v171
	v_mul_f32_e32 v128, v128, v172
	v_mul_f32_e32 v129, v129, v173
	v_cvt_pk_bf16_f32 v168, v126, v127
	v_cvt_pk_bf16_f32 v169, v128, v129
	global_store_dwordx4 v148, v[166:169], s[8:9]
	s_add_u32 s8, s8, 0xf000
	s_addc_u32 s9, s9, 0
	ds_write2_b32 v146, v82, v66 offset0:0 offset1:32
	ds_write2_b32 v146, v83, v67 offset0:68 offset1:100
	ds_write2_b32 v146, v84, v68 offset0:136 offset1:168
	ds_write2_b32 v146, v85, v69 offset0:204 offset1:236
	v_add_u32_e32 v146, 0x880, v146
	ds_write2_b32 v146, v86, v70 offset0:0 offset1:32
	ds_write2_b32 v146, v87, v71 offset0:68 offset1:100
	ds_write2_b32 v146, v88, v72 offset0:136 offset1:168
	ds_write2_b32 v146, v89, v73 offset0:204 offset1:236
	v_add_u32_e32 v146, 0x880, v146
	ds_write2_b32 v146, v90, v74 offset0:0 offset1:32
	ds_write2_b32 v146, v91, v75 offset0:68 offset1:100
	ds_write2_b32 v146, v92, v76 offset0:136 offset1:168
	ds_write2_b32 v146, v93, v77 offset0:204 offset1:236
	v_add_u32_e32 v146, 0x880, v146
	ds_write2_b32 v146, v94, v78 offset0:0 offset1:32
	ds_write2_b32 v146, v95, v79 offset0:68 offset1:100
	ds_write2_b32 v146, v96, v80 offset0:136 offset1:168
	ds_write2_b32 v146, v97, v81 offset0:204 offset1:236
	v_subrev_u32_e32 v146, 0x1980, v146
	s_waitcnt lgkmcnt(0)
	ds_read_b128 v[66:69], v147
	ds_read_b128 v[70:73], v147 offset:16
	ds_read_b128 v[74:77], v147 offset:2176
	ds_read_b128 v[78:81], v147 offset:2192
	ds_read_b128 v[82:85], v147 offset:4352
	ds_read_b128 v[86:89], v147 offset:4368
	ds_read_b128 v[90:93], v147 offset:6528
	ds_read_b128 v[94:97], v147 offset:6544
	s_waitcnt lgkmcnt(6)
	v_mul_f32_e32 v170, 0xbfb8aa3b, v66
	v_mul_f32_e32 v171, 0xbfb8aa3b, v67
	v_mul_f32_e32 v172, 0xbfb8aa3b, v68
	v_mul_f32_e32 v173, 0xbfb8aa3b, v69
	v_exp_f32_e32 v170, v170
	v_exp_f32_e32 v171, v171
	v_exp_f32_e32 v172, v172
	v_exp_f32_e32 v173, v173
	v_add_f32_e32 v170, 1.0, v170
	v_add_f32_e32 v171, 1.0, v171
	v_add_f32_e32 v172, 1.0, v172
	v_add_f32_e32 v173, 1.0, v173
	v_rcp_f32_e32 v170, v170
	v_rcp_f32_e32 v171, v171
	v_rcp_f32_e32 v172, v172
	v_rcp_f32_e32 v173, v173
	s_nop 0
	v_mul_f32_e32 v66, v66, v170
	v_mul_f32_e32 v67, v67, v171
	v_mul_f32_e32 v68, v68, v172
	v_mul_f32_e32 v69, v69, v173
	v_cvt_pk_bf16_f32 v154, v66, v67
	v_cvt_pk_bf16_f32 v155, v68, v69
	v_mul_f32_e32 v170, 0xbfb8aa3b, v70
	v_mul_f32_e32 v171, 0xbfb8aa3b, v71
	v_mul_f32_e32 v172, 0xbfb8aa3b, v72
	v_mul_f32_e32 v173, 0xbfb8aa3b, v73
	v_exp_f32_e32 v170, v170
	v_exp_f32_e32 v171, v171
	v_exp_f32_e32 v172, v172
	v_exp_f32_e32 v173, v173
	v_add_f32_e32 v170, 1.0, v170
	v_add_f32_e32 v171, 1.0, v171
	v_add_f32_e32 v172, 1.0, v172
	v_add_f32_e32 v173, 1.0, v173
	v_rcp_f32_e32 v170, v170
	v_rcp_f32_e32 v171, v171
	v_rcp_f32_e32 v172, v172
	v_rcp_f32_e32 v173, v173
	s_nop 0
	v_mul_f32_e32 v70, v70, v170
	v_mul_f32_e32 v71, v71, v171
	v_mul_f32_e32 v72, v72, v172
	v_mul_f32_e32 v73, v73, v173
	v_cvt_pk_bf16_f32 v156, v70, v71
	v_cvt_pk_bf16_f32 v157, v72, v73
	global_store_dwordx4 v148, v[154:157], s[8:9]
	s_add_u32 s8, s8, 0xf000
	s_addc_u32 s9, s9, 0
	s_waitcnt lgkmcnt(4)
	v_mul_f32_e32 v170, 0xbfb8aa3b, v74
	v_mul_f32_e32 v171, 0xbfb8aa3b, v75
	v_mul_f32_e32 v172, 0xbfb8aa3b, v76
	v_mul_f32_e32 v173, 0xbfb8aa3b, v77
	v_exp_f32_e32 v170, v170
	v_exp_f32_e32 v171, v171
	v_exp_f32_e32 v172, v172
	v_exp_f32_e32 v173, v173
	v_add_f32_e32 v170, 1.0, v170
	v_add_f32_e32 v171, 1.0, v171
	v_add_f32_e32 v172, 1.0, v172
	v_add_f32_e32 v173, 1.0, v173
	v_rcp_f32_e32 v170, v170
	v_rcp_f32_e32 v171, v171
	v_rcp_f32_e32 v172, v172
	v_rcp_f32_e32 v173, v173
	s_nop 0
	v_mul_f32_e32 v74, v74, v170
	v_mul_f32_e32 v75, v75, v171
	v_mul_f32_e32 v76, v76, v172
	v_mul_f32_e32 v77, v77, v173
	v_cvt_pk_bf16_f32 v158, v74, v75
	v_cvt_pk_bf16_f32 v159, v76, v77
	v_mul_f32_e32 v170, 0xbfb8aa3b, v78
	v_mul_f32_e32 v171, 0xbfb8aa3b, v79
	v_mul_f32_e32 v172, 0xbfb8aa3b, v80
	v_mul_f32_e32 v173, 0xbfb8aa3b, v81
	v_exp_f32_e32 v170, v170
	v_exp_f32_e32 v171, v171
	v_exp_f32_e32 v172, v172
	v_exp_f32_e32 v173, v173
	v_add_f32_e32 v170, 1.0, v170
	v_add_f32_e32 v171, 1.0, v171
	v_add_f32_e32 v172, 1.0, v172
	v_add_f32_e32 v173, 1.0, v173
	v_rcp_f32_e32 v170, v170
	v_rcp_f32_e32 v171, v171
	v_rcp_f32_e32 v172, v172
	v_rcp_f32_e32 v173, v173
	s_nop 0
	v_mul_f32_e32 v78, v78, v170
	v_mul_f32_e32 v79, v79, v171
	v_mul_f32_e32 v80, v80, v172
	v_mul_f32_e32 v81, v81, v173
	v_cvt_pk_bf16_f32 v160, v78, v79
	v_cvt_pk_bf16_f32 v161, v80, v81
	global_store_dwordx4 v148, v[158:161], s[8:9]
	s_add_u32 s8, s8, 0xf000
	s_addc_u32 s9, s9, 0
	s_waitcnt lgkmcnt(2)
	v_mul_f32_e32 v170, 0xbfb8aa3b, v82
	v_mul_f32_e32 v171, 0xbfb8aa3b, v83
	v_mul_f32_e32 v172, 0xbfb8aa3b, v84
	v_mul_f32_e32 v173, 0xbfb8aa3b, v85
	v_exp_f32_e32 v170, v170
	v_exp_f32_e32 v171, v171
	v_exp_f32_e32 v172, v172
	v_exp_f32_e32 v173, v173
	v_add_f32_e32 v170, 1.0, v170
	v_add_f32_e32 v171, 1.0, v171
	v_add_f32_e32 v172, 1.0, v172
	v_add_f32_e32 v173, 1.0, v173
	v_rcp_f32_e32 v170, v170
	v_rcp_f32_e32 v171, v171
	v_rcp_f32_e32 v172, v172
	v_rcp_f32_e32 v173, v173
	s_nop 0
	v_mul_f32_e32 v82, v82, v170
	v_mul_f32_e32 v83, v83, v171
	v_mul_f32_e32 v84, v84, v172
	v_mul_f32_e32 v85, v85, v173
	v_cvt_pk_bf16_f32 v162, v82, v83
	v_cvt_pk_bf16_f32 v163, v84, v85
	v_mul_f32_e32 v170, 0xbfb8aa3b, v86
	v_mul_f32_e32 v171, 0xbfb8aa3b, v87
	v_mul_f32_e32 v172, 0xbfb8aa3b, v88
	v_mul_f32_e32 v173, 0xbfb8aa3b, v89
	v_exp_f32_e32 v170, v170
	v_exp_f32_e32 v171, v171
	v_exp_f32_e32 v172, v172
	v_exp_f32_e32 v173, v173
	v_add_f32_e32 v170, 1.0, v170
	v_add_f32_e32 v171, 1.0, v171
	v_add_f32_e32 v172, 1.0, v172
	v_add_f32_e32 v173, 1.0, v173
	v_rcp_f32_e32 v170, v170
	v_rcp_f32_e32 v171, v171
	v_rcp_f32_e32 v172, v172
	v_rcp_f32_e32 v173, v173
	s_nop 0
	v_mul_f32_e32 v86, v86, v170
	v_mul_f32_e32 v87, v87, v171
	v_mul_f32_e32 v88, v88, v172
	v_mul_f32_e32 v89, v89, v173
	v_cvt_pk_bf16_f32 v164, v86, v87
	v_cvt_pk_bf16_f32 v165, v88, v89
	global_store_dwordx4 v148, v[162:165], s[8:9]
	s_add_u32 s8, s8, 0xf000
	s_addc_u32 s9, s9, 0
	s_waitcnt lgkmcnt(0)
	v_mul_f32_e32 v170, 0xbfb8aa3b, v90
	v_mul_f32_e32 v171, 0xbfb8aa3b, v91
	v_mul_f32_e32 v172, 0xbfb8aa3b, v92
	v_mul_f32_e32 v173, 0xbfb8aa3b, v93
	v_exp_f32_e32 v170, v170
	v_exp_f32_e32 v171, v171
	v_exp_f32_e32 v172, v172
	v_exp_f32_e32 v173, v173
	v_add_f32_e32 v170, 1.0, v170
	v_add_f32_e32 v171, 1.0, v171
	v_add_f32_e32 v172, 1.0, v172
	v_add_f32_e32 v173, 1.0, v173
	v_rcp_f32_e32 v170, v170
	v_rcp_f32_e32 v171, v171
	v_rcp_f32_e32 v172, v172
	v_rcp_f32_e32 v173, v173
	s_nop 0
	v_mul_f32_e32 v90, v90, v170
	v_mul_f32_e32 v91, v91, v171
	v_mul_f32_e32 v92, v92, v172
	v_mul_f32_e32 v93, v93, v173
	v_cvt_pk_bf16_f32 v166, v90, v91
	v_cvt_pk_bf16_f32 v167, v92, v93
	v_mul_f32_e32 v170, 0xbfb8aa3b, v94
	v_mul_f32_e32 v171, 0xbfb8aa3b, v95
	v_mul_f32_e32 v172, 0xbfb8aa3b, v96
	v_mul_f32_e32 v173, 0xbfb8aa3b, v97
	v_exp_f32_e32 v170, v170
	v_exp_f32_e32 v171, v171
	v_exp_f32_e32 v172, v172
	v_exp_f32_e32 v173, v173
	v_add_f32_e32 v170, 1.0, v170
	v_add_f32_e32 v171, 1.0, v171
	v_add_f32_e32 v172, 1.0, v172
	v_add_f32_e32 v173, 1.0, v173
	v_rcp_f32_e32 v170, v170
	v_rcp_f32_e32 v171, v171
	v_rcp_f32_e32 v172, v172
	v_rcp_f32_e32 v173, v173
	s_nop 0
	v_mul_f32_e32 v94, v94, v170
	v_mul_f32_e32 v95, v95, v171
	v_mul_f32_e32 v96, v96, v172
	v_mul_f32_e32 v97, v97, v173
	v_cvt_pk_bf16_f32 v168, v94, v95
	v_cvt_pk_bf16_f32 v169, v96, v97
	global_store_dwordx4 v148, v[166:169], s[8:9]
	s_add_u32 s8, s8, 0xf000
	s_addc_u32 s9, s9, 0
	ds_write2_b32 v146, v50, v34 offset0:0 offset1:32
	ds_write2_b32 v146, v51, v35 offset0:68 offset1:100
	ds_write2_b32 v146, v52, v36 offset0:136 offset1:168
	ds_write2_b32 v146, v53, v37 offset0:204 offset1:236
	v_add_u32_e32 v146, 0x880, v146
	ds_write2_b32 v146, v54, v38 offset0:0 offset1:32
	ds_write2_b32 v146, v55, v39 offset0:68 offset1:100
	ds_write2_b32 v146, v56, v40 offset0:136 offset1:168
	ds_write2_b32 v146, v57, v41 offset0:204 offset1:236
	v_add_u32_e32 v146, 0x880, v146
	ds_write2_b32 v146, v58, v42 offset0:0 offset1:32
	ds_write2_b32 v146, v59, v43 offset0:68 offset1:100
	ds_write2_b32 v146, v60, v44 offset0:136 offset1:168
	ds_write2_b32 v146, v61, v45 offset0:204 offset1:236
	v_add_u32_e32 v146, 0x880, v146
	ds_write2_b32 v146, v62, v46 offset0:0 offset1:32
	ds_write2_b32 v146, v63, v47 offset0:68 offset1:100
	ds_write2_b32 v146, v64, v48 offset0:136 offset1:168
	ds_write2_b32 v146, v65, v49 offset0:204 offset1:236
	v_subrev_u32_e32 v146, 0x1980, v146
	s_waitcnt lgkmcnt(0)
	ds_read_b128 v[34:37], v147
	ds_read_b128 v[38:41], v147 offset:16
	ds_read_b128 v[42:45], v147 offset:2176
	ds_read_b128 v[46:49], v147 offset:2192
	ds_read_b128 v[50:53], v147 offset:4352
	ds_read_b128 v[54:57], v147 offset:4368
	ds_read_b128 v[58:61], v147 offset:6528
	ds_read_b128 v[62:65], v147 offset:6544
	s_waitcnt lgkmcnt(6)
	v_mul_f32_e32 v170, 0xbfb8aa3b, v34
	v_mul_f32_e32 v171, 0xbfb8aa3b, v35
	v_mul_f32_e32 v172, 0xbfb8aa3b, v36
	v_mul_f32_e32 v173, 0xbfb8aa3b, v37
	v_exp_f32_e32 v170, v170
	v_exp_f32_e32 v171, v171
	v_exp_f32_e32 v172, v172
	v_exp_f32_e32 v173, v173
	v_add_f32_e32 v170, 1.0, v170
	v_add_f32_e32 v171, 1.0, v171
	v_add_f32_e32 v172, 1.0, v172
	v_add_f32_e32 v173, 1.0, v173
	v_rcp_f32_e32 v170, v170
	v_rcp_f32_e32 v171, v171
	v_rcp_f32_e32 v172, v172
	v_rcp_f32_e32 v173, v173
	s_nop 0
	v_mul_f32_e32 v34, v34, v170
	v_mul_f32_e32 v35, v35, v171
	v_mul_f32_e32 v36, v36, v172
	v_mul_f32_e32 v37, v37, v173
	v_cvt_pk_bf16_f32 v154, v34, v35
	v_cvt_pk_bf16_f32 v155, v36, v37
	v_mul_f32_e32 v170, 0xbfb8aa3b, v38
	v_mul_f32_e32 v171, 0xbfb8aa3b, v39
	v_mul_f32_e32 v172, 0xbfb8aa3b, v40
	v_mul_f32_e32 v173, 0xbfb8aa3b, v41
	v_exp_f32_e32 v170, v170
	v_exp_f32_e32 v171, v171
	v_exp_f32_e32 v172, v172
	v_exp_f32_e32 v173, v173
	v_add_f32_e32 v170, 1.0, v170
	v_add_f32_e32 v171, 1.0, v171
	v_add_f32_e32 v172, 1.0, v172
	v_add_f32_e32 v173, 1.0, v173
	v_rcp_f32_e32 v170, v170
	v_rcp_f32_e32 v171, v171
	v_rcp_f32_e32 v172, v172
	v_rcp_f32_e32 v173, v173
	s_nop 0
	v_mul_f32_e32 v38, v38, v170
	v_mul_f32_e32 v39, v39, v171
	v_mul_f32_e32 v40, v40, v172
	v_mul_f32_e32 v41, v41, v173
	v_cvt_pk_bf16_f32 v156, v38, v39
	v_cvt_pk_bf16_f32 v157, v40, v41
	global_store_dwordx4 v148, v[154:157], s[8:9]
	s_add_u32 s8, s8, 0xf000
	s_addc_u32 s9, s9, 0
	s_waitcnt lgkmcnt(4)
	v_mul_f32_e32 v170, 0xbfb8aa3b, v42
	v_mul_f32_e32 v171, 0xbfb8aa3b, v43
	v_mul_f32_e32 v172, 0xbfb8aa3b, v44
	v_mul_f32_e32 v173, 0xbfb8aa3b, v45
	v_exp_f32_e32 v170, v170
	v_exp_f32_e32 v171, v171
	v_exp_f32_e32 v172, v172
	v_exp_f32_e32 v173, v173
	v_add_f32_e32 v170, 1.0, v170
	v_add_f32_e32 v171, 1.0, v171
	v_add_f32_e32 v172, 1.0, v172
	v_add_f32_e32 v173, 1.0, v173
	v_rcp_f32_e32 v170, v170
	v_rcp_f32_e32 v171, v171
	v_rcp_f32_e32 v172, v172
	v_rcp_f32_e32 v173, v173
	s_nop 0
	v_mul_f32_e32 v42, v42, v170
	v_mul_f32_e32 v43, v43, v171
	v_mul_f32_e32 v44, v44, v172
	v_mul_f32_e32 v45, v45, v173
	v_cvt_pk_bf16_f32 v158, v42, v43
	v_cvt_pk_bf16_f32 v159, v44, v45
	v_mul_f32_e32 v170, 0xbfb8aa3b, v46
	v_mul_f32_e32 v171, 0xbfb8aa3b, v47
	v_mul_f32_e32 v172, 0xbfb8aa3b, v48
	v_mul_f32_e32 v173, 0xbfb8aa3b, v49
	v_exp_f32_e32 v170, v170
	v_exp_f32_e32 v171, v171
	v_exp_f32_e32 v172, v172
	v_exp_f32_e32 v173, v173
	v_add_f32_e32 v170, 1.0, v170
	v_add_f32_e32 v171, 1.0, v171
	v_add_f32_e32 v172, 1.0, v172
	v_add_f32_e32 v173, 1.0, v173
	v_rcp_f32_e32 v170, v170
	v_rcp_f32_e32 v171, v171
	v_rcp_f32_e32 v172, v172
	v_rcp_f32_e32 v173, v173
	s_nop 0
	v_mul_f32_e32 v46, v46, v170
	v_mul_f32_e32 v47, v47, v171
	v_mul_f32_e32 v48, v48, v172
	v_mul_f32_e32 v49, v49, v173
	v_cvt_pk_bf16_f32 v160, v46, v47
	v_cvt_pk_bf16_f32 v161, v48, v49
	global_store_dwordx4 v148, v[158:161], s[8:9]
	s_add_u32 s8, s8, 0xf000
	s_addc_u32 s9, s9, 0
	s_waitcnt lgkmcnt(2)
	v_mul_f32_e32 v170, 0xbfb8aa3b, v50
	v_mul_f32_e32 v171, 0xbfb8aa3b, v51
	v_mul_f32_e32 v172, 0xbfb8aa3b, v52
	v_mul_f32_e32 v173, 0xbfb8aa3b, v53
	v_exp_f32_e32 v170, v170
	v_exp_f32_e32 v171, v171
	v_exp_f32_e32 v172, v172
	v_exp_f32_e32 v173, v173
	v_add_f32_e32 v170, 1.0, v170
	v_add_f32_e32 v171, 1.0, v171
	v_add_f32_e32 v172, 1.0, v172
	v_add_f32_e32 v173, 1.0, v173
	v_rcp_f32_e32 v170, v170
	v_rcp_f32_e32 v171, v171
	v_rcp_f32_e32 v172, v172
	v_rcp_f32_e32 v173, v173
	s_nop 0
	v_mul_f32_e32 v50, v50, v170
	v_mul_f32_e32 v51, v51, v171
	v_mul_f32_e32 v52, v52, v172
	v_mul_f32_e32 v53, v53, v173
	v_cvt_pk_bf16_f32 v162, v50, v51
	v_cvt_pk_bf16_f32 v163, v52, v53
	v_mul_f32_e32 v170, 0xbfb8aa3b, v54
	v_mul_f32_e32 v171, 0xbfb8aa3b, v55
	v_mul_f32_e32 v172, 0xbfb8aa3b, v56
	v_mul_f32_e32 v173, 0xbfb8aa3b, v57
	v_exp_f32_e32 v170, v170
	v_exp_f32_e32 v171, v171
	v_exp_f32_e32 v172, v172
	v_exp_f32_e32 v173, v173
	v_add_f32_e32 v170, 1.0, v170
	v_add_f32_e32 v171, 1.0, v171
	v_add_f32_e32 v172, 1.0, v172
	v_add_f32_e32 v173, 1.0, v173
	v_rcp_f32_e32 v170, v170
	v_rcp_f32_e32 v171, v171
	v_rcp_f32_e32 v172, v172
	v_rcp_f32_e32 v173, v173
	s_nop 0
	v_mul_f32_e32 v54, v54, v170
	v_mul_f32_e32 v55, v55, v171
	v_mul_f32_e32 v56, v56, v172
	v_mul_f32_e32 v57, v57, v173
	v_cvt_pk_bf16_f32 v164, v54, v55
	v_cvt_pk_bf16_f32 v165, v56, v57
	global_store_dwordx4 v148, v[162:165], s[8:9]
	s_add_u32 s8, s8, 0xf000
	s_addc_u32 s9, s9, 0
	s_waitcnt lgkmcnt(0)
	v_mul_f32_e32 v170, 0xbfb8aa3b, v58
	v_mul_f32_e32 v171, 0xbfb8aa3b, v59
	v_mul_f32_e32 v172, 0xbfb8aa3b, v60
	v_mul_f32_e32 v173, 0xbfb8aa3b, v61
	v_exp_f32_e32 v170, v170
	v_exp_f32_e32 v171, v171
	v_exp_f32_e32 v172, v172
	v_exp_f32_e32 v173, v173
	v_add_f32_e32 v170, 1.0, v170
	v_add_f32_e32 v171, 1.0, v171
	v_add_f32_e32 v172, 1.0, v172
	v_add_f32_e32 v173, 1.0, v173
	v_rcp_f32_e32 v170, v170
	v_rcp_f32_e32 v171, v171
	v_rcp_f32_e32 v172, v172
	v_rcp_f32_e32 v173, v173
	s_nop 0
	v_mul_f32_e32 v58, v58, v170
	v_mul_f32_e32 v59, v59, v171
	v_mul_f32_e32 v60, v60, v172
	v_mul_f32_e32 v61, v61, v173
	v_cvt_pk_bf16_f32 v166, v58, v59
	v_cvt_pk_bf16_f32 v167, v60, v61
	v_mul_f32_e32 v170, 0xbfb8aa3b, v62
	v_mul_f32_e32 v171, 0xbfb8aa3b, v63
	v_mul_f32_e32 v172, 0xbfb8aa3b, v64
	v_mul_f32_e32 v173, 0xbfb8aa3b, v65
	v_exp_f32_e32 v170, v170
	v_exp_f32_e32 v171, v171
	v_exp_f32_e32 v172, v172
	v_exp_f32_e32 v173, v173
	v_add_f32_e32 v170, 1.0, v170
	v_add_f32_e32 v171, 1.0, v171
	v_add_f32_e32 v172, 1.0, v172
	v_add_f32_e32 v173, 1.0, v173
	v_rcp_f32_e32 v170, v170
	v_rcp_f32_e32 v171, v171
	v_rcp_f32_e32 v172, v172
	v_rcp_f32_e32 v173, v173
	s_nop 0
	v_mul_f32_e32 v62, v62, v170
	v_mul_f32_e32 v63, v63, v171
	v_mul_f32_e32 v64, v64, v172
	v_mul_f32_e32 v65, v65, v173
	v_cvt_pk_bf16_f32 v168, v62, v63
	v_cvt_pk_bf16_f32 v169, v64, v65
	global_store_dwordx4 v148, v[166:169], s[8:9]
	s_add_u32 s8, s8, 0xf000
	s_addc_u32 s9, s9, 0
	ds_write2_b32 v146, v18, v2 offset0:0 offset1:32
	ds_write2_b32 v146, v19, v3 offset0:68 offset1:100
	ds_write2_b32 v146, v20, v4 offset0:136 offset1:168
	ds_write2_b32 v146, v21, v5 offset0:204 offset1:236
	v_add_u32_e32 v146, 0x880, v146
	ds_write2_b32 v146, v22, v6 offset0:0 offset1:32
	ds_write2_b32 v146, v23, v7 offset0:68 offset1:100
	ds_write2_b32 v146, v24, v8 offset0:136 offset1:168
	ds_write2_b32 v146, v25, v9 offset0:204 offset1:236
	v_add_u32_e32 v146, 0x880, v146
	ds_write2_b32 v146, v26, v10 offset0:0 offset1:32
	ds_write2_b32 v146, v27, v11 offset0:68 offset1:100
	ds_write2_b32 v146, v28, v12 offset0:136 offset1:168
	ds_write2_b32 v146, v29, v13 offset0:204 offset1:236
	v_add_u32_e32 v146, 0x880, v146
	ds_write2_b32 v146, v30, v14 offset0:0 offset1:32
	ds_write2_b32 v146, v31, v15 offset0:68 offset1:100
	ds_write2_b32 v146, v32, v16 offset0:136 offset1:168
	ds_write2_b32 v146, v33, v17 offset0:204 offset1:236
	v_subrev_u32_e32 v146, 0x1980, v146
	s_waitcnt lgkmcnt(0)
	ds_read_b128 v[2:5], v147
	ds_read_b128 v[6:9], v147 offset:16
	ds_read_b128 v[10:13], v147 offset:2176
	ds_read_b128 v[14:17], v147 offset:2192
	ds_read_b128 v[18:21], v147 offset:4352
	ds_read_b128 v[22:25], v147 offset:4368
	ds_read_b128 v[26:29], v147 offset:6528
	ds_read_b128 v[30:33], v147 offset:6544
	s_waitcnt lgkmcnt(0)
	s_barrier
	v_mul_f32_e32 v170, 0xbfb8aa3b, v2
	v_mul_f32_e32 v171, 0xbfb8aa3b, v3
	v_mul_f32_e32 v172, 0xbfb8aa3b, v4
	v_mul_f32_e32 v173, 0xbfb8aa3b, v5
	v_exp_f32_e32 v170, v170
	v_exp_f32_e32 v171, v171
	v_exp_f32_e32 v172, v172
	v_exp_f32_e32 v173, v173
	v_add_f32_e32 v170, 1.0, v170
	v_add_f32_e32 v171, 1.0, v171
	v_add_f32_e32 v172, 1.0, v172
	v_add_f32_e32 v173, 1.0, v173
	v_rcp_f32_e32 v170, v170
	v_rcp_f32_e32 v171, v171
	v_rcp_f32_e32 v172, v172
	v_rcp_f32_e32 v173, v173
	s_nop 0
	v_mul_f32_e32 v2, v2, v170
	v_mul_f32_e32 v3, v3, v171
	v_mul_f32_e32 v4, v4, v172
	v_mul_f32_e32 v5, v5, v173
	v_cvt_pk_bf16_f32 v154, v2, v3
	v_cvt_pk_bf16_f32 v155, v4, v5
	v_mul_f32_e32 v170, 0xbfb8aa3b, v6
	v_mul_f32_e32 v171, 0xbfb8aa3b, v7
	v_mul_f32_e32 v172, 0xbfb8aa3b, v8
	v_mul_f32_e32 v173, 0xbfb8aa3b, v9
	v_exp_f32_e32 v170, v170
	v_exp_f32_e32 v171, v171
	v_exp_f32_e32 v172, v172
	v_exp_f32_e32 v173, v173
	v_add_f32_e32 v170, 1.0, v170
	v_add_f32_e32 v171, 1.0, v171
	v_add_f32_e32 v172, 1.0, v172
	v_add_f32_e32 v173, 1.0, v173
	v_rcp_f32_e32 v170, v170
	v_rcp_f32_e32 v171, v171
	v_rcp_f32_e32 v172, v172
	v_rcp_f32_e32 v173, v173
	s_nop 0
	v_mul_f32_e32 v6, v6, v170
	v_mul_f32_e32 v7, v7, v171
	v_mul_f32_e32 v8, v8, v172
	v_mul_f32_e32 v9, v9, v173
	v_cvt_pk_bf16_f32 v156, v6, v7
	v_cvt_pk_bf16_f32 v157, v8, v9
	global_store_dwordx4 v148, v[154:157], s[8:9]
	s_add_u32 s8, s8, 0xf000
	s_addc_u32 s9, s9, 0
	v_mul_f32_e32 v170, 0xbfb8aa3b, v10
	v_mul_f32_e32 v171, 0xbfb8aa3b, v11
	v_mul_f32_e32 v172, 0xbfb8aa3b, v12
	v_mul_f32_e32 v173, 0xbfb8aa3b, v13
	v_exp_f32_e32 v170, v170
	v_exp_f32_e32 v171, v171
	v_exp_f32_e32 v172, v172
	v_exp_f32_e32 v173, v173
	v_add_f32_e32 v170, 1.0, v170
	v_add_f32_e32 v171, 1.0, v171
	v_add_f32_e32 v172, 1.0, v172
	v_add_f32_e32 v173, 1.0, v173
	v_rcp_f32_e32 v170, v170
	v_rcp_f32_e32 v171, v171
	v_rcp_f32_e32 v172, v172
	v_rcp_f32_e32 v173, v173
	s_nop 0
	v_mul_f32_e32 v10, v10, v170
	v_mul_f32_e32 v11, v11, v171
	v_mul_f32_e32 v12, v12, v172
	v_mul_f32_e32 v13, v13, v173
	v_cvt_pk_bf16_f32 v158, v10, v11
	v_cvt_pk_bf16_f32 v159, v12, v13
	v_mul_f32_e32 v170, 0xbfb8aa3b, v14
	v_mul_f32_e32 v171, 0xbfb8aa3b, v15
	v_mul_f32_e32 v172, 0xbfb8aa3b, v16
	v_mul_f32_e32 v173, 0xbfb8aa3b, v17
	v_exp_f32_e32 v170, v170
	v_exp_f32_e32 v171, v171
	v_exp_f32_e32 v172, v172
	v_exp_f32_e32 v173, v173
	v_add_f32_e32 v170, 1.0, v170
	v_add_f32_e32 v171, 1.0, v171
	v_add_f32_e32 v172, 1.0, v172
	v_add_f32_e32 v173, 1.0, v173
	v_rcp_f32_e32 v170, v170
	v_rcp_f32_e32 v171, v171
	v_rcp_f32_e32 v172, v172
	v_rcp_f32_e32 v173, v173
	s_nop 0
	v_mul_f32_e32 v14, v14, v170
	v_mul_f32_e32 v15, v15, v171
	v_mul_f32_e32 v16, v16, v172
	v_mul_f32_e32 v17, v17, v173
	v_cvt_pk_bf16_f32 v160, v14, v15
	v_cvt_pk_bf16_f32 v161, v16, v17
	global_store_dwordx4 v148, v[158:161], s[8:9]
	s_add_u32 s8, s8, 0xf000
	s_addc_u32 s9, s9, 0
	v_mul_f32_e32 v170, 0xbfb8aa3b, v18
	v_mul_f32_e32 v171, 0xbfb8aa3b, v19
	v_mul_f32_e32 v172, 0xbfb8aa3b, v20
	v_mul_f32_e32 v173, 0xbfb8aa3b, v21
	v_exp_f32_e32 v170, v170
	v_exp_f32_e32 v171, v171
	v_exp_f32_e32 v172, v172
	v_exp_f32_e32 v173, v173
	v_add_f32_e32 v170, 1.0, v170
	v_add_f32_e32 v171, 1.0, v171
	v_add_f32_e32 v172, 1.0, v172
	v_add_f32_e32 v173, 1.0, v173
	v_rcp_f32_e32 v170, v170
	v_rcp_f32_e32 v171, v171
	v_rcp_f32_e32 v172, v172
	v_rcp_f32_e32 v173, v173
	s_nop 0
	v_mul_f32_e32 v18, v18, v170
	v_mul_f32_e32 v19, v19, v171
	v_mul_f32_e32 v20, v20, v172
	v_mul_f32_e32 v21, v21, v173
	v_cvt_pk_bf16_f32 v162, v18, v19
	v_cvt_pk_bf16_f32 v163, v20, v21
	v_mul_f32_e32 v170, 0xbfb8aa3b, v22
	v_mul_f32_e32 v171, 0xbfb8aa3b, v23
	v_mul_f32_e32 v172, 0xbfb8aa3b, v24
	v_mul_f32_e32 v173, 0xbfb8aa3b, v25
	v_exp_f32_e32 v170, v170
	v_exp_f32_e32 v171, v171
	v_exp_f32_e32 v172, v172
	v_exp_f32_e32 v173, v173
	v_add_f32_e32 v170, 1.0, v170
	v_add_f32_e32 v171, 1.0, v171
	v_add_f32_e32 v172, 1.0, v172
	v_add_f32_e32 v173, 1.0, v173
	v_rcp_f32_e32 v170, v170
	v_rcp_f32_e32 v171, v171
	v_rcp_f32_e32 v172, v172
	v_rcp_f32_e32 v173, v173
	s_nop 0
	v_mul_f32_e32 v22, v22, v170
	v_mul_f32_e32 v23, v23, v171
	v_mul_f32_e32 v24, v24, v172
	v_mul_f32_e32 v25, v25, v173
	v_cvt_pk_bf16_f32 v164, v22, v23
	v_cvt_pk_bf16_f32 v165, v24, v25
	global_store_dwordx4 v148, v[162:165], s[8:9]
	s_add_u32 s8, s8, 0xf000
	s_addc_u32 s9, s9, 0
	v_mul_f32_e32 v170, 0xbfb8aa3b, v26
	v_mul_f32_e32 v171, 0xbfb8aa3b, v27
	v_mul_f32_e32 v172, 0xbfb8aa3b, v28
	v_mul_f32_e32 v173, 0xbfb8aa3b, v29
	v_exp_f32_e32 v170, v170
	v_exp_f32_e32 v171, v171
	v_exp_f32_e32 v172, v172
	v_exp_f32_e32 v173, v173
	v_add_f32_e32 v170, 1.0, v170
	v_add_f32_e32 v171, 1.0, v171
	v_add_f32_e32 v172, 1.0, v172
	v_add_f32_e32 v173, 1.0, v173
	v_rcp_f32_e32 v170, v170
	v_rcp_f32_e32 v171, v171
	v_rcp_f32_e32 v172, v172
	v_rcp_f32_e32 v173, v173
	s_nop 0
	v_mul_f32_e32 v26, v26, v170
	v_mul_f32_e32 v27, v27, v171
	v_mul_f32_e32 v28, v28, v172
	v_mul_f32_e32 v29, v29, v173
	v_cvt_pk_bf16_f32 v166, v26, v27
	v_cvt_pk_bf16_f32 v167, v28, v29
	v_mul_f32_e32 v170, 0xbfb8aa3b, v30
	v_mul_f32_e32 v171, 0xbfb8aa3b, v31
	v_mul_f32_e32 v172, 0xbfb8aa3b, v32
	v_mul_f32_e32 v173, 0xbfb8aa3b, v33
	v_exp_f32_e32 v170, v170
	v_exp_f32_e32 v171, v171
	v_exp_f32_e32 v172, v172
	v_exp_f32_e32 v173, v173
	v_add_f32_e32 v170, 1.0, v170
	v_add_f32_e32 v171, 1.0, v171
	v_add_f32_e32 v172, 1.0, v172
	v_add_f32_e32 v173, 1.0, v173
	v_rcp_f32_e32 v170, v170
	v_rcp_f32_e32 v171, v171
	v_rcp_f32_e32 v172, v172
	v_rcp_f32_e32 v173, v173
	s_nop 0
	v_mul_f32_e32 v30, v30, v170
	v_mul_f32_e32 v31, v31, v171
	v_mul_f32_e32 v32, v32, v172
	v_mul_f32_e32 v33, v33, v173
	v_cvt_pk_bf16_f32 v168, v30, v31
	v_cvt_pk_bf16_f32 v169, v32, v33
	global_store_dwordx4 v148, v[166:169], s[8:9]
	s_add_u32 s8, s8, 0xf000
	s_addc_u32 s9, s9, 0
	s_add_i32 s70, s70, s10
	s_cmp_lt_i32 s70, s71
	s_cbranch_scc0 .LBB0_209
	s_branch .LBB0_215
